# P0: hand-written double-buffered x->bf16 row loop and pipelined gate/up weight conversion, both with nontemporal (streaming) stores
# speedup vs baseline: 1.0229x; 1.0111x over previous
.LBB0_55:
	s_and_b64 vcc, exec, s[38:39]
	s_cbranch_vccz .LBB0_21
	v_readlane_b32 s0, v254, 1
	v_readlane_b32 s1, v254, 2
	s_mov_b32 s94, s7
	s_andn2_b64 vcc, exec, s[0:1]
	s_cbranch_vccnz .LBB0_88
	s_branch .Lmy_cvgu0

.Lmy_cvgu0:
	v_and_b32_e32 v172, 63, v252
	v_lshrrev_b32_e32 v173, 5, v172
	v_and_b32_e32 v174, 31, v172
	v_mul_u32_u24_e32 v175, 0x1600, v173
	v_add_lshl_u32 v176, v175, v174, 2
	v_lshrrev_b32_e32 v175, 6, v252
	s_nop 0
	v_readfirstlane_b32 s32, v175
	v_readlane_b32 s91, v253, 0
	s_mul_i32 s100, s32, 0x2100
	s_lshl_b32 s91, s91, 3
	s_add_u32 s91, s91, s32
	v_mul_u32_u24_e32 v175, 33, v173
	v_add_u32_e32 v175, v175, v174
	v_lshl_add_u32 v177, v175, 2, s100
	v_and_b32_e32 v173, 7, v172
	v_lshrrev_b32_e32 v174, 3, v172
	v_mul_u32_u24_e32 v175, 0x108, v173
	v_add_u32_e32 v175, v175, v174
	v_lshl_add_u32 v178, v175, 2, s100
	v_lshlrev_b32_e32 v175, 4, v173
	v_lshl_add_u32 v255, v174, 12, v175
	s_cmp_ge_u32 s91, 0x1600
	s_cselect_b32 s100, 0x1600, 0
	s_cselect_b32 s101, 13, 11
	s_cselect_b32 vcc_hi, 0x80, 0
	s_sub_u32 s100, s91, s100
	s_mul_i32 s32, s100, 0xba2f
	s_lshr_b32 s32, s32, 23
	s_mul_i32 vcc_lo, s32, 0xb0
	s_sub_u32 vcc_lo, s100, vcc_lo
	v_readlane_b32 s42, v253, s101
	s_add_u32 s101, s101, 1
	v_readlane_b32 s43, v253, s101
	v_readlane_b32 s98, v253, 9
	v_readlane_b32 s99, v253, 10
	v_readlane_b32 s54, v253, 63
	v_readlane_b32 s55, v254, 0
	s_mul_i32 s100, s32, 0x160000
	s_add_u32 s42, s42, s100
	s_addc_u32 s43, s43, 0
	s_lshl_b32 s100, vcc_lo, 7
	s_add_u32 s42, s42, s100
	s_addc_u32 s43, s43, 0
	s_lshl_b32 s100, s32, 8
	s_add_u32 s98, s98, s100
	s_addc_u32 s99, s99, 0
	s_lshr_b32 s100, vcc_lo, 2
	s_lshl_b32 s100, s100, 8
	s_and_b32 s101, vcc_lo, 3
	s_lshl_b32 s101, s101, 5
	s_add_u32 s100, s100, s101
	s_add_u32 s100, s100, vcc_hi
	s_lshl_b32 s100, s100, 12
	s_lshl_b32 s101, s32, 7
	s_add_u32 s100, s100, s101
	s_add_u32 s54, s54, s100
	s_addc_u32 s55, s55, 0
	s_add_u32 s54, s54, 0x2700000
	s_addc_u32 s55, s55, 0
	v_and_b32_e32 v172, 0x70, v255
	v_lshlrev_b32_e32 v172, 1, v172
	global_load_dwordx4 v[244:247], v172, s[98:99]
	global_load_dwordx4 v[248:251], v172, s[98:99] offset:16
	global_load_dword v180, v176, s[42:43] nt
	s_add_u32 s42, s42, 0xb000
	s_addc_u32 s43, s43, 0
	global_load_dword v181, v176, s[42:43] nt
	s_add_u32 s42, s42, 0xb000
	s_addc_u32 s43, s43, 0
	global_load_dword v182, v176, s[42:43] nt
	s_add_u32 s42, s42, 0xb000
	s_addc_u32 s43, s43, 0
	global_load_dword v183, v176, s[42:43] nt
	s_add_u32 s42, s42, 0xb000
	s_addc_u32 s43, s43, 0
	global_load_dword v184, v176, s[42:43] nt
	s_add_u32 s42, s42, 0xb000
	s_addc_u32 s43, s43, 0
	global_load_dword v185, v176, s[42:43] nt
	s_add_u32 s42, s42, 0xb000
	s_addc_u32 s43, s43, 0
	global_load_dword v186, v176, s[42:43] nt
	s_add_u32 s42, s42, 0xb000
	s_addc_u32 s43, s43, 0
	global_load_dword v187, v176, s[42:43] nt
	s_add_u32 s42, s42, 0xb000
	s_addc_u32 s43, s43, 0
	global_load_dword v188, v176, s[42:43] nt
	s_add_u32 s42, s42, 0xb000
	s_addc_u32 s43, s43, 0
	global_load_dword v189, v176, s[42:43] nt
	s_add_u32 s42, s42, 0xb000
	s_addc_u32 s43, s43, 0
	global_load_dword v190, v176, s[42:43] nt
	s_add_u32 s42, s42, 0xb000
	s_addc_u32 s43, s43, 0
	global_load_dword v191, v176, s[42:43] nt
	s_add_u32 s42, s42, 0xb000
	s_addc_u32 s43, s43, 0
	global_load_dword v192, v176, s[42:43] nt
	s_add_u32 s42, s42, 0xb000
	s_addc_u32 s43, s43, 0
	global_load_dword v193, v176, s[42:43] nt
	s_add_u32 s42, s42, 0xb000
	s_addc_u32 s43, s43, 0
	global_load_dword v194, v176, s[42:43] nt
	s_add_u32 s42, s42, 0xb000
	s_addc_u32 s43, s43, 0
	global_load_dword v195, v176, s[42:43] nt
	s_add_u32 s42, s42, 0xb000
	s_addc_u32 s43, s43, 0
	global_load_dword v196, v176, s[42:43] nt
	s_add_u32 s42, s42, 0xb000
	s_addc_u32 s43, s43, 0
	global_load_dword v197, v176, s[42:43] nt
	s_add_u32 s42, s42, 0xb000
	s_addc_u32 s43, s43, 0
	global_load_dword v198, v176, s[42:43] nt
	s_add_u32 s42, s42, 0xb000
	s_addc_u32 s43, s43, 0
	global_load_dword v199, v176, s[42:43] nt
	s_add_u32 s42, s42, 0xb000
	s_addc_u32 s43, s43, 0
	global_load_dword v200, v176, s[42:43] nt
	s_add_u32 s42, s42, 0xb000
	s_addc_u32 s43, s43, 0
	global_load_dword v201, v176, s[42:43] nt
	s_add_u32 s42, s42, 0xb000
	s_addc_u32 s43, s43, 0
	global_load_dword v202, v176, s[42:43] nt
	s_add_u32 s42, s42, 0xb000
	s_addc_u32 s43, s43, 0
	global_load_dword v203, v176, s[42:43] nt
	s_add_u32 s42, s42, 0xb000
	s_addc_u32 s43, s43, 0
	global_load_dword v204, v176, s[42:43] nt
	s_add_u32 s42, s42, 0xb000
	s_addc_u32 s43, s43, 0
	global_load_dword v205, v176, s[42:43] nt
	s_add_u32 s42, s42, 0xb000
	s_addc_u32 s43, s43, 0
	global_load_dword v206, v176, s[42:43] nt
	s_add_u32 s42, s42, 0xb000
	s_addc_u32 s43, s43, 0
	global_load_dword v207, v176, s[42:43] nt
	s_add_u32 s42, s42, 0xb000
	s_addc_u32 s43, s43, 0
	global_load_dword v208, v176, s[42:43] nt
	s_add_u32 s42, s42, 0xb000
	s_addc_u32 s43, s43, 0
	global_load_dword v209, v176, s[42:43] nt
	s_add_u32 s42, s42, 0xb000
	s_addc_u32 s43, s43, 0
	global_load_dword v210, v176, s[42:43] nt
	s_add_u32 s42, s42, 0xb000
	s_addc_u32 s43, s43, 0
	global_load_dword v211, v176, s[42:43] nt
	s_waitcnt vmcnt(0)
	s_branch .Lmy_cvgu0_body
.Lmy_cvgu0_top:
	s_waitcnt vmcnt(4)
.Lmy_cvgu0_body:
	s_mov_b64 s[44:45], s[54:55]
	ds_write_b32 v177, v180 offset:0
	ds_write_b32 v177, v181 offset:264
	ds_write_b32 v177, v182 offset:528
	ds_write_b32 v177, v183 offset:792
	ds_write_b32 v177, v184 offset:1056
	ds_write_b32 v177, v185 offset:1320
	ds_write_b32 v177, v186 offset:1584
	ds_write_b32 v177, v187 offset:1848
	ds_write_b32 v177, v188 offset:2112
	ds_write_b32 v177, v189 offset:2376
	ds_write_b32 v177, v190 offset:2640
	ds_write_b32 v177, v191 offset:2904
	ds_write_b32 v177, v192 offset:3168
	ds_write_b32 v177, v193 offset:3432
	ds_write_b32 v177, v194 offset:3696
	ds_write_b32 v177, v195 offset:3960
	ds_write_b32 v177, v196 offset:4224
	ds_write_b32 v177, v197 offset:4488
	ds_write_b32 v177, v198 offset:4752
	ds_write_b32 v177, v199 offset:5016
	ds_write_b32 v177, v200 offset:5280
	ds_write_b32 v177, v201 offset:5544
	ds_write_b32 v177, v202 offset:5808
	ds_write_b32 v177, v203 offset:6072
	ds_write_b32 v177, v204 offset:6336
	ds_write_b32 v177, v205 offset:6600
	ds_write_b32 v177, v206 offset:6864
	ds_write_b32 v177, v207 offset:7128
	ds_write_b32 v177, v208 offset:7392
	ds_write_b32 v177, v209 offset:7656
	ds_write_b32 v177, v210 offset:7920
	ds_write_b32 v177, v211 offset:8184
	v_mov_b64_e32 v[164:165], v[244:245]
	v_mov_b64_e32 v[166:167], v[246:247]
	v_mov_b64_e32 v[168:169], v[248:249]
	v_mov_b64_e32 v[170:171], v[250:251]
	s_add_u32 s91, s91, 0x800
	s_cmp_lt_u32 s91, 0x2c00
	s_cbranch_scc0 .Lmy_cvgu0_nonext
	s_cmp_ge_u32 s91, 0x1600
	s_cselect_b32 s100, 0x1600, 0
	s_cselect_b32 s101, 13, 11
	s_cselect_b32 vcc_hi, 0x80, 0
	s_sub_u32 s100, s91, s100
	s_mul_i32 s32, s100, 0xba2f
	s_lshr_b32 s32, s32, 23
	s_mul_i32 vcc_lo, s32, 0xb0
	s_sub_u32 vcc_lo, s100, vcc_lo
	v_readlane_b32 s42, v253, s101
	s_add_u32 s101, s101, 1
	v_readlane_b32 s43, v253, s101
	v_readlane_b32 s98, v253, 9
	v_readlane_b32 s99, v253, 10
	v_readlane_b32 s54, v253, 63
	v_readlane_b32 s55, v254, 0
	s_mul_i32 s100, s32, 0x160000
	s_add_u32 s42, s42, s100
	s_addc_u32 s43, s43, 0
	s_lshl_b32 s100, vcc_lo, 7
	s_add_u32 s42, s42, s100
	s_addc_u32 s43, s43, 0
	s_lshl_b32 s100, s32, 8
	s_add_u32 s98, s98, s100
	s_addc_u32 s99, s99, 0
	s_lshr_b32 s100, vcc_lo, 2
	s_lshl_b32 s100, s100, 8
	s_and_b32 s101, vcc_lo, 3
	s_lshl_b32 s101, s101, 5
	s_add_u32 s100, s100, s101
	s_add_u32 s100, s100, vcc_hi
	s_lshl_b32 s100, s100, 12
	s_lshl_b32 s101, s32, 7
	s_add_u32 s100, s100, s101
	s_add_u32 s54, s54, s100
	s_addc_u32 s55, s55, 0
	s_add_u32 s54, s54, 0x2700000
	s_addc_u32 s55, s55, 0
	v_and_b32_e32 v172, 0x70, v255
	v_lshlrev_b32_e32 v172, 1, v172
	global_load_dwordx4 v[244:247], v172, s[98:99]
	global_load_dwordx4 v[248:251], v172, s[98:99] offset:16
	global_load_dword v180, v176, s[42:43] nt
	s_add_u32 s42, s42, 0xb000
	s_addc_u32 s43, s43, 0
	global_load_dword v181, v176, s[42:43] nt
	s_add_u32 s42, s42, 0xb000
	s_addc_u32 s43, s43, 0
	global_load_dword v182, v176, s[42:43] nt
	s_add_u32 s42, s42, 0xb000
	s_addc_u32 s43, s43, 0
	global_load_dword v183, v176, s[42:43] nt
	s_add_u32 s42, s42, 0xb000
	s_addc_u32 s43, s43, 0
	global_load_dword v184, v176, s[42:43] nt
	s_add_u32 s42, s42, 0xb000
	s_addc_u32 s43, s43, 0
	global_load_dword v185, v176, s[42:43] nt
	s_add_u32 s42, s42, 0xb000
	s_addc_u32 s43, s43, 0
	global_load_dword v186, v176, s[42:43] nt
	s_add_u32 s42, s42, 0xb000
	s_addc_u32 s43, s43, 0
	global_load_dword v187, v176, s[42:43] nt
	s_add_u32 s42, s42, 0xb000
	s_addc_u32 s43, s43, 0
	global_load_dword v188, v176, s[42:43] nt
	s_add_u32 s42, s42, 0xb000
	s_addc_u32 s43, s43, 0
	global_load_dword v189, v176, s[42:43] nt
	s_add_u32 s42, s42, 0xb000
	s_addc_u32 s43, s43, 0
	global_load_dword v190, v176, s[42:43] nt
	s_add_u32 s42, s42, 0xb000
	s_addc_u32 s43, s43, 0
	global_load_dword v191, v176, s[42:43] nt
	s_add_u32 s42, s42, 0xb000
	s_addc_u32 s43, s43, 0
	global_load_dword v192, v176, s[42:43] nt
	s_add_u32 s42, s42, 0xb000
	s_addc_u32 s43, s43, 0
	global_load_dword v193, v176, s[42:43] nt
	s_add_u32 s42, s42, 0xb000
	s_addc_u32 s43, s43, 0
	global_load_dword v194, v176, s[42:43] nt
	s_add_u32 s42, s42, 0xb000
	s_addc_u32 s43, s43, 0
	global_load_dword v195, v176, s[42:43] nt
	s_add_u32 s42, s42, 0xb000
	s_addc_u32 s43, s43, 0
	global_load_dword v196, v176, s[42:43] nt
	s_add_u32 s42, s42, 0xb000
	s_addc_u32 s43, s43, 0
	global_load_dword v197, v176, s[42:43] nt
	s_add_u32 s42, s42, 0xb000
	s_addc_u32 s43, s43, 0
	global_load_dword v198, v176, s[42:43] nt
	s_add_u32 s42, s42, 0xb000
	s_addc_u32 s43, s43, 0
	global_load_dword v199, v176, s[42:43] nt
	s_add_u32 s42, s42, 0xb000
	s_addc_u32 s43, s43, 0
	global_load_dword v200, v176, s[42:43] nt
	s_add_u32 s42, s42, 0xb000
	s_addc_u32 s43, s43, 0
	global_load_dword v201, v176, s[42:43] nt
	s_add_u32 s42, s42, 0xb000
	s_addc_u32 s43, s43, 0
	global_load_dword v202, v176, s[42:43] nt
	s_add_u32 s42, s42, 0xb000
	s_addc_u32 s43, s43, 0
	global_load_dword v203, v176, s[42:43] nt
	s_add_u32 s42, s42, 0xb000
	s_addc_u32 s43, s43, 0
	global_load_dword v204, v176, s[42:43] nt
	s_add_u32 s42, s42, 0xb000
	s_addc_u32 s43, s43, 0
	global_load_dword v205, v176, s[42:43] nt
	s_add_u32 s42, s42, 0xb000
	s_addc_u32 s43, s43, 0
	global_load_dword v206, v176, s[42:43] nt
	s_add_u32 s42, s42, 0xb000
	s_addc_u32 s43, s43, 0
	global_load_dword v207, v176, s[42:43] nt
	s_add_u32 s42, s42, 0xb000
	s_addc_u32 s43, s43, 0
	global_load_dword v208, v176, s[42:43] nt
	s_add_u32 s42, s42, 0xb000
	s_addc_u32 s43, s43, 0
	global_load_dword v209, v176, s[42:43] nt
	s_add_u32 s42, s42, 0xb000
	s_addc_u32 s43, s43, 0
	global_load_dword v210, v176, s[42:43] nt
	s_add_u32 s42, s42, 0xb000
	s_addc_u32 s43, s43, 0
	global_load_dword v211, v176, s[42:43] nt
.Lmy_cvgu0_nonext:
	s_waitcnt lgkmcnt(0)
	ds_read2_b32 v[212:213], v178 offset0:0 offset1:33
	ds_read2_b32 v[214:215], v178 offset0:66 offset1:99
	ds_read2_b32 v[216:217], v178 offset0:132 offset1:165
	ds_read2_b32 v[218:219], v178 offset0:198 offset1:231
	ds_read2_b32 v[220:221], v178 offset0:8 offset1:41
	ds_read2_b32 v[222:223], v178 offset0:74 offset1:107
	ds_read2_b32 v[224:225], v178 offset0:140 offset1:173
	ds_read2_b32 v[226:227], v178 offset0:206 offset1:239
	ds_read2_b32 v[228:229], v178 offset0:16 offset1:49
	ds_read2_b32 v[230:231], v178 offset0:82 offset1:115
	ds_read2_b32 v[232:233], v178 offset0:148 offset1:181
	ds_read2_b32 v[234:235], v178 offset0:214 offset1:247
	s_waitcnt lgkmcnt(8)
	v_pk_mul_f32 v[212:213], v[212:213], v[164:165]
	v_pk_mul_f32 v[214:215], v[214:215], v[166:167]
	v_pk_mul_f32 v[216:217], v[216:217], v[168:169]
	v_pk_mul_f32 v[218:219], v[218:219], v[170:171]
	v_bfe_u32 v172, v212, 16, 1
	v_bfe_u32 v173, v213, 16, 1
	v_add3_u32 v172, v212, v172, s75
	v_add3_u32 v173, v213, v173, s75
	v_lshrrev_b32_e32 v172, 16, v172
	v_and_or_b32 v212, v173, s76, v172
	v_bfe_u32 v172, v214, 16, 1
	v_bfe_u32 v173, v215, 16, 1
	v_add3_u32 v172, v214, v172, s75
	v_add3_u32 v173, v215, v173, s75
	v_lshrrev_b32_e32 v172, 16, v172
	v_and_or_b32 v213, v173, s76, v172
	v_bfe_u32 v172, v216, 16, 1
	v_bfe_u32 v173, v217, 16, 1
	v_add3_u32 v172, v216, v172, s75
	v_add3_u32 v173, v217, v173, s75
	v_lshrrev_b32_e32 v172, 16, v172
	v_and_or_b32 v214, v173, s76, v172
	v_bfe_u32 v172, v218, 16, 1
	v_bfe_u32 v173, v219, 16, 1
	v_add3_u32 v172, v218, v172, s75
	v_add3_u32 v173, v219, v173, s75
	v_lshrrev_b32_e32 v172, 16, v172
	v_and_or_b32 v215, v173, s76, v172
	global_store_dwordx4 v255, v[212:215], s[44:45] nt
	s_add_u32 s44, s44, 0x8000
	s_addc_u32 s45, s45, 0
	ds_read2_b32 v[236:237], v178 offset0:24 offset1:57
	ds_read2_b32 v[238:239], v178 offset0:90 offset1:123
	ds_read2_b32 v[240:241], v178 offset0:156 offset1:189
	ds_read2_b32 v[242:243], v178 offset0:222 offset1:255
	s_waitcnt lgkmcnt(8)
	v_pk_mul_f32 v[220:221], v[220:221], v[164:165]
	v_pk_mul_f32 v[222:223], v[222:223], v[166:167]
	v_pk_mul_f32 v[224:225], v[224:225], v[168:169]
	v_pk_mul_f32 v[226:227], v[226:227], v[170:171]
	v_bfe_u32 v172, v220, 16, 1
	v_bfe_u32 v173, v221, 16, 1
	v_add3_u32 v172, v220, v172, s75
	v_add3_u32 v173, v221, v173, s75
	v_lshrrev_b32_e32 v172, 16, v172
	v_and_or_b32 v220, v173, s76, v172
	v_bfe_u32 v172, v222, 16, 1
	v_bfe_u32 v173, v223, 16, 1
	v_add3_u32 v172, v222, v172, s75
	v_add3_u32 v173, v223, v173, s75
	v_lshrrev_b32_e32 v172, 16, v172
	v_and_or_b32 v221, v173, s76, v172
	v_bfe_u32 v172, v224, 16, 1
	v_bfe_u32 v173, v225, 16, 1
	v_add3_u32 v172, v224, v172, s75
	v_add3_u32 v173, v225, v173, s75
	v_lshrrev_b32_e32 v172, 16, v172
	v_and_or_b32 v222, v173, s76, v172
	v_bfe_u32 v172, v226, 16, 1
	v_bfe_u32 v173, v227, 16, 1
	v_add3_u32 v172, v226, v172, s75
	v_add3_u32 v173, v227, v173, s75
	v_lshrrev_b32_e32 v172, 16, v172
	v_and_or_b32 v223, v173, s76, v172
	global_store_dwordx4 v255, v[220:223], s[44:45] nt
	s_add_u32 s44, s44, 0x8000
	s_addc_u32 s45, s45, 0
	s_waitcnt lgkmcnt(4)
	v_pk_mul_f32 v[228:229], v[228:229], v[164:165]
	v_pk_mul_f32 v[230:231], v[230:231], v[166:167]
	v_pk_mul_f32 v[232:233], v[232:233], v[168:169]
	v_pk_mul_f32 v[234:235], v[234:235], v[170:171]
	v_bfe_u32 v172, v228, 16, 1
	v_bfe_u32 v173, v229, 16, 1
	v_add3_u32 v172, v228, v172, s75
	v_add3_u32 v173, v229, v173, s75
	v_lshrrev_b32_e32 v172, 16, v172
	v_and_or_b32 v228, v173, s76, v172
	v_bfe_u32 v172, v230, 16, 1
	v_bfe_u32 v173, v231, 16, 1
	v_add3_u32 v172, v230, v172, s75
	v_add3_u32 v173, v231, v173, s75
	v_lshrrev_b32_e32 v172, 16, v172
	v_and_or_b32 v229, v173, s76, v172
	v_bfe_u32 v172, v232, 16, 1
	v_bfe_u32 v173, v233, 16, 1
	v_add3_u32 v172, v232, v172, s75
	v_add3_u32 v173, v233, v173, s75
	v_lshrrev_b32_e32 v172, 16, v172
	v_and_or_b32 v230, v173, s76, v172
	v_bfe_u32 v172, v234, 16, 1
	v_bfe_u32 v173, v235, 16, 1
	v_add3_u32 v172, v234, v172, s75
	v_add3_u32 v173, v235, v173, s75
	v_lshrrev_b32_e32 v172, 16, v172
	v_and_or_b32 v231, v173, s76, v172
	global_store_dwordx4 v255, v[228:231], s[44:45] nt
	s_add_u32 s44, s44, 0x8000
	s_addc_u32 s45, s45, 0
	s_waitcnt lgkmcnt(0)
	v_pk_mul_f32 v[236:237], v[236:237], v[164:165]
	v_pk_mul_f32 v[238:239], v[238:239], v[166:167]
	v_pk_mul_f32 v[240:241], v[240:241], v[168:169]
	v_pk_mul_f32 v[242:243], v[242:243], v[170:171]
	v_bfe_u32 v172, v236, 16, 1
	v_bfe_u32 v173, v237, 16, 1
	v_add3_u32 v172, v236, v172, s75
	v_add3_u32 v173, v237, v173, s75
	v_lshrrev_b32_e32 v172, 16, v172
	v_and_or_b32 v236, v173, s76, v172
	v_bfe_u32 v172, v238, 16, 1
	v_bfe_u32 v173, v239, 16, 1
	v_add3_u32 v172, v238, v172, s75
	v_add3_u32 v173, v239, v173, s75
	v_lshrrev_b32_e32 v172, 16, v172
	v_and_or_b32 v237, v173, s76, v172
	v_bfe_u32 v172, v240, 16, 1
	v_bfe_u32 v173, v241, 16, 1
	v_add3_u32 v172, v240, v172, s75
	v_add3_u32 v173, v241, v173, s75
	v_lshrrev_b32_e32 v172, 16, v172
	v_and_or_b32 v238, v173, s76, v172
	v_bfe_u32 v172, v242, 16, 1
	v_bfe_u32 v173, v243, 16, 1
	v_add3_u32 v172, v242, v172, s75
	v_add3_u32 v173, v243, v173, s75
	v_lshrrev_b32_e32 v172, 16, v172
	v_and_or_b32 v239, v173, s76, v172
	global_store_dwordx4 v255, v[236:239], s[44:45] nt
	s_cmp_lt_u32 s91, 0x2c00
	s_cbranch_scc1 .Lmy_cvgu0_top

.Lmy_xrow0:
	v_and_b32_e32 v176, 63, v252
	v_lshlrev_b32_e32 v164, 4, v176
	v_add_u32_e32 v165, 0x1000, v164
	v_lshlrev_b32_e32 v166, 3, v176
	v_xor_b32_e32 v167, 1, v176
	v_lshlrev_b32_e32 v167, 2, v167
	v_xor_b32_e32 v168, 2, v176
	v_lshlrev_b32_e32 v168, 2, v168
	v_xor_b32_e32 v169, 4, v176
	v_lshlrev_b32_e32 v169, 2, v169
	v_xor_b32_e32 v170, 8, v176
	v_lshlrev_b32_e32 v170, 2, v170
	v_xor_b32_e32 v171, 16, v176
	v_lshlrev_b32_e32 v171, 2, v171
	v_xor_b32_e32 v172, 32, v176
	v_lshlrev_b32_e32 v172, 2, v172
	v_mov_b32_e32 v173, 0
	v_lshrrev_b32_e32 v177, 6, v252
	s_nop 0
	v_readfirstlane_b32 s91, v177
	v_readlane_b32 s32, v253, 0
	s_lshl_b32 s32, s32, 3
	s_add_u32 s91, s91, s32
	v_readlane_b32 s98, v253, 7
	v_readlane_b32 s99, v253, 8
	v_readlane_b32 s100, v253, 63
	v_readlane_b32 s101, v254, 0
	s_lshl_b32 s32, s91, 13
	s_add_u32 s98, s98, s32
	s_addc_u32 s99, s99, 0
	s_lshl_b32 s32, s91, 2
	s_add_u32 s54, s100, s32
	s_addc_u32 s55, s101, 0
	s_lshl_b32 s32, s91, 12
	s_add_u32 s100, s100, s32
	s_addc_u32 s101, s101, 0
	s_add_u32 s100, s100, 0x8a00000
	s_addc_u32 s101, s101, 0
	s_mov_b32 s32, 0x7060302
	global_load_dwordx4 v[180:183], v164, s[98:99] offset:0 nt
	global_load_dwordx4 v[184:187], v164, s[98:99] offset:1024 nt
	global_load_dwordx4 v[188:191], v164, s[98:99] offset:2048 nt
	global_load_dwordx4 v[192:195], v164, s[98:99] offset:3072 nt
	global_load_dwordx4 v[196:199], v165, s[98:99] offset:0 nt
	global_load_dwordx4 v[200:203], v165, s[98:99] offset:1024 nt
	global_load_dwordx4 v[204:207], v165, s[98:99] offset:2048 nt
	global_load_dwordx4 v[208:211], v165, s[98:99] offset:3072 nt
	s_add_u32 s98, s98, 0x1000000
	s_addc_u32 s99, s99, 0
	global_load_dwordx4 v[212:215], v164, s[98:99] offset:0 nt
	global_load_dwordx4 v[216:219], v164, s[98:99] offset:1024 nt
	global_load_dwordx4 v[220:223], v164, s[98:99] offset:2048 nt
	global_load_dwordx4 v[224:227], v164, s[98:99] offset:3072 nt
	global_load_dwordx4 v[228:231], v165, s[98:99] offset:0 nt
	global_load_dwordx4 v[232:235], v165, s[98:99] offset:1024 nt
	global_load_dwordx4 v[236:239], v165, s[98:99] offset:2048 nt
	global_load_dwordx4 v[240:243], v165, s[98:99] offset:3072 nt
	s_add_u32 s98, s98, 0x1000000
	s_addc_u32 s99, s99, 0
	s_waitcnt vmcnt(8)
	v_mul_f32_e32 v244, v181, v181
	v_mul_f32_e32 v245, v183, v183
	v_fmac_f32_e32 v244, v180, v180
	v_fmac_f32_e32 v245, v182, v182
	v_add_f32_e32 v174, v244, v245
	v_bfe_u32 v246, v180, 16, 1
	v_bfe_u32 v247, v181, 16, 1
	v_bfe_u32 v248, v182, 16, 1
	v_bfe_u32 v249, v183, 16, 1
	v_add3_u32 v246, v180, v246, s75
	v_add3_u32 v247, v181, v247, s75
	v_add3_u32 v248, v182, v248, s75
	v_add3_u32 v249, v183, v249, s75
	v_perm_b32 v250, v247, v246, s32
	v_perm_b32 v251, v249, v248, s32
	global_store_dwordx2 v166, v[250:251], s[100:101] offset:0 nt
	v_mul_f32_e32 v244, v185, v185
	v_mul_f32_e32 v245, v187, v187
	v_fmac_f32_e32 v244, v184, v184
	v_fmac_f32_e32 v245, v186, v186
	v_add_f32_e32 v244, v244, v245
	v_add_f32_e32 v174, v174, v244
	v_bfe_u32 v246, v184, 16, 1
	v_bfe_u32 v247, v185, 16, 1
	v_bfe_u32 v248, v186, 16, 1
	v_bfe_u32 v249, v187, 16, 1
	v_add3_u32 v246, v184, v246, s75
	v_add3_u32 v247, v185, v247, s75
	v_add3_u32 v248, v186, v248, s75
	v_add3_u32 v249, v187, v249, s75
	v_perm_b32 v250, v247, v246, s32
	v_perm_b32 v251, v249, v248, s32
	global_store_dwordx2 v166, v[250:251], s[100:101] offset:512 nt
	v_mul_f32_e32 v244, v189, v189
	v_mul_f32_e32 v245, v191, v191
	v_fmac_f32_e32 v244, v188, v188
	v_fmac_f32_e32 v245, v190, v190
	v_add_f32_e32 v244, v244, v245
	v_add_f32_e32 v174, v174, v244
	v_bfe_u32 v246, v188, 16, 1
	v_bfe_u32 v247, v189, 16, 1
	v_bfe_u32 v248, v190, 16, 1
	v_bfe_u32 v249, v191, 16, 1
	v_add3_u32 v246, v188, v246, s75
	v_add3_u32 v247, v189, v247, s75
	v_add3_u32 v248, v190, v248, s75
	v_add3_u32 v249, v191, v249, s75
	v_perm_b32 v250, v247, v246, s32
	v_perm_b32 v251, v249, v248, s32
	global_store_dwordx2 v166, v[250:251], s[100:101] offset:1024 nt
	v_mul_f32_e32 v244, v193, v193
	v_mul_f32_e32 v245, v195, v195
	v_fmac_f32_e32 v244, v192, v192
	v_fmac_f32_e32 v245, v194, v194
	v_add_f32_e32 v244, v244, v245
	v_add_f32_e32 v174, v174, v244
	v_bfe_u32 v246, v192, 16, 1
	v_bfe_u32 v247, v193, 16, 1
	v_bfe_u32 v248, v194, 16, 1
	v_bfe_u32 v249, v195, 16, 1
	v_add3_u32 v246, v192, v246, s75
	v_add3_u32 v247, v193, v247, s75
	v_add3_u32 v248, v194, v248, s75
	v_add3_u32 v249, v195, v249, s75
	v_perm_b32 v250, v247, v246, s32
	v_perm_b32 v251, v249, v248, s32
	global_store_dwordx2 v166, v[250:251], s[100:101] offset:1536 nt
	v_mul_f32_e32 v244, v197, v197
	v_mul_f32_e32 v245, v199, v199
	v_fmac_f32_e32 v244, v196, v196
	v_fmac_f32_e32 v245, v198, v198
	v_add_f32_e32 v244, v244, v245
	v_add_f32_e32 v174, v174, v244
	v_bfe_u32 v246, v196, 16, 1
	v_bfe_u32 v247, v197, 16, 1
	v_bfe_u32 v248, v198, 16, 1
	v_bfe_u32 v249, v199, 16, 1
	v_add3_u32 v246, v196, v246, s75
	v_add3_u32 v247, v197, v247, s75
	v_add3_u32 v248, v198, v248, s75
	v_add3_u32 v249, v199, v249, s75
	v_perm_b32 v250, v247, v246, s32
	v_perm_b32 v251, v249, v248, s32
	global_store_dwordx2 v166, v[250:251], s[100:101] offset:2048 nt
	v_mul_f32_e32 v244, v201, v201
	v_mul_f32_e32 v245, v203, v203
	v_fmac_f32_e32 v244, v200, v200
	v_fmac_f32_e32 v245, v202, v202
	v_add_f32_e32 v244, v244, v245
	v_add_f32_e32 v174, v174, v244
	v_bfe_u32 v246, v200, 16, 1
	v_bfe_u32 v247, v201, 16, 1
	v_bfe_u32 v248, v202, 16, 1
	v_bfe_u32 v249, v203, 16, 1
	v_add3_u32 v246, v200, v246, s75
	v_add3_u32 v247, v201, v247, s75
	v_add3_u32 v248, v202, v248, s75
	v_add3_u32 v249, v203, v249, s75
	v_perm_b32 v250, v247, v246, s32
	v_perm_b32 v251, v249, v248, s32
	global_store_dwordx2 v166, v[250:251], s[100:101] offset:2560 nt
	v_mul_f32_e32 v244, v205, v205
	v_mul_f32_e32 v245, v207, v207
	v_fmac_f32_e32 v244, v204, v204
	v_fmac_f32_e32 v245, v206, v206
	v_add_f32_e32 v244, v244, v245
	v_add_f32_e32 v174, v174, v244
	v_bfe_u32 v246, v204, 16, 1
	v_bfe_u32 v247, v205, 16, 1
	v_bfe_u32 v248, v206, 16, 1
	v_bfe_u32 v249, v207, 16, 1
	v_add3_u32 v246, v204, v246, s75
	v_add3_u32 v247, v205, v247, s75
	v_add3_u32 v248, v206, v248, s75
	v_add3_u32 v249, v207, v249, s75
	v_perm_b32 v250, v247, v246, s32
	v_perm_b32 v251, v249, v248, s32
	global_store_dwordx2 v166, v[250:251], s[100:101] offset:3072 nt
	v_mul_f32_e32 v244, v209, v209
	v_mul_f32_e32 v245, v211, v211
	v_fmac_f32_e32 v244, v208, v208
	v_fmac_f32_e32 v245, v210, v210
	v_add_f32_e32 v244, v244, v245
	v_add_f32_e32 v174, v174, v244
	v_bfe_u32 v246, v208, 16, 1
	v_bfe_u32 v247, v209, 16, 1
	v_bfe_u32 v248, v210, 16, 1
	v_bfe_u32 v249, v211, 16, 1
	v_add3_u32 v246, v208, v246, s75
	v_add3_u32 v247, v209, v247, s75
	v_add3_u32 v248, v210, v248, s75
	v_add3_u32 v249, v211, v249, s75
	v_perm_b32 v250, v247, v246, s32
	v_perm_b32 v251, v249, v248, s32
	global_store_dwordx2 v166, v[250:251], s[100:101] offset:3584 nt
	s_add_u32 s100, s100, 0x800000
	s_addc_u32 s101, s101, 0
	global_load_dwordx4 v[180:183], v164, s[98:99] offset:0 nt
	global_load_dwordx4 v[184:187], v164, s[98:99] offset:1024 nt
	global_load_dwordx4 v[188:191], v164, s[98:99] offset:2048 nt
	global_load_dwordx4 v[192:195], v164, s[98:99] offset:3072 nt
	global_load_dwordx4 v[196:199], v165, s[98:99] offset:0 nt
	global_load_dwordx4 v[200:203], v165, s[98:99] offset:1024 nt
	global_load_dwordx4 v[204:207], v165, s[98:99] offset:2048 nt
	global_load_dwordx4 v[208:211], v165, s[98:99] offset:3072 nt
	s_add_u32 s98, s98, 0x1000000
	s_addc_u32 s99, s99, 0
	s_waitcnt vmcnt(16)
	v_mul_f32_e32 v244, v213, v213
	v_mul_f32_e32 v245, v215, v215
	v_fmac_f32_e32 v244, v212, v212
	v_fmac_f32_e32 v245, v214, v214
	v_add_f32_e32 v175, v244, v245
	v_bfe_u32 v246, v212, 16, 1
	v_bfe_u32 v247, v213, 16, 1
	v_bfe_u32 v248, v214, 16, 1
	v_bfe_u32 v249, v215, 16, 1
	v_add3_u32 v246, v212, v246, s75
	v_add3_u32 v247, v213, v247, s75
	v_add3_u32 v248, v214, v248, s75
	v_add3_u32 v249, v215, v249, s75
	v_perm_b32 v250, v247, v246, s32
	v_perm_b32 v251, v249, v248, s32
	global_store_dwordx2 v166, v[250:251], s[100:101] offset:0 nt
	v_mul_f32_e32 v244, v217, v217
	v_mul_f32_e32 v245, v219, v219
	v_fmac_f32_e32 v244, v216, v216
	v_fmac_f32_e32 v245, v218, v218
	v_add_f32_e32 v244, v244, v245
	v_add_f32_e32 v175, v175, v244
	v_bfe_u32 v246, v216, 16, 1
	v_bfe_u32 v247, v217, 16, 1
	v_bfe_u32 v248, v218, 16, 1
	v_bfe_u32 v249, v219, 16, 1
	v_add3_u32 v246, v216, v246, s75
	v_add3_u32 v247, v217, v247, s75
	v_add3_u32 v248, v218, v248, s75
	v_add3_u32 v249, v219, v249, s75
	v_perm_b32 v250, v247, v246, s32
	v_perm_b32 v251, v249, v248, s32
	global_store_dwordx2 v166, v[250:251], s[100:101] offset:512 nt
	v_mul_f32_e32 v244, v221, v221
	v_mul_f32_e32 v245, v223, v223
	v_fmac_f32_e32 v244, v220, v220
	v_fmac_f32_e32 v245, v222, v222
	v_add_f32_e32 v244, v244, v245
	v_add_f32_e32 v175, v175, v244
	v_bfe_u32 v246, v220, 16, 1
	v_bfe_u32 v247, v221, 16, 1
	v_bfe_u32 v248, v222, 16, 1
	v_bfe_u32 v249, v223, 16, 1
	v_add3_u32 v246, v220, v246, s75
	v_add3_u32 v247, v221, v247, s75
	v_add3_u32 v248, v222, v248, s75
	v_add3_u32 v249, v223, v249, s75
	v_perm_b32 v250, v247, v246, s32
	v_perm_b32 v251, v249, v248, s32
	global_store_dwordx2 v166, v[250:251], s[100:101] offset:1024 nt
	v_mul_f32_e32 v244, v225, v225
	v_mul_f32_e32 v245, v227, v227
	v_fmac_f32_e32 v244, v224, v224
	v_fmac_f32_e32 v245, v226, v226
	v_add_f32_e32 v244, v244, v245
	v_add_f32_e32 v175, v175, v244
	v_bfe_u32 v246, v224, 16, 1
	v_bfe_u32 v247, v225, 16, 1
	v_bfe_u32 v248, v226, 16, 1
	v_bfe_u32 v249, v227, 16, 1
	v_add3_u32 v246, v224, v246, s75
	v_add3_u32 v247, v225, v247, s75
	v_add3_u32 v248, v226, v248, s75
	v_add3_u32 v249, v227, v249, s75
	v_perm_b32 v250, v247, v246, s32
	v_perm_b32 v251, v249, v248, s32
	global_store_dwordx2 v166, v[250:251], s[100:101] offset:1536 nt
	v_mul_f32_e32 v244, v229, v229
	v_mul_f32_e32 v245, v231, v231
	v_fmac_f32_e32 v244, v228, v228
	v_fmac_f32_e32 v245, v230, v230
	v_add_f32_e32 v244, v244, v245
	v_add_f32_e32 v175, v175, v244
	v_bfe_u32 v246, v228, 16, 1
	v_bfe_u32 v247, v229, 16, 1
	v_bfe_u32 v248, v230, 16, 1
	v_bfe_u32 v249, v231, 16, 1
	v_add3_u32 v246, v228, v246, s75
	v_add3_u32 v247, v229, v247, s75
	v_add3_u32 v248, v230, v248, s75
	v_add3_u32 v249, v231, v249, s75
	v_perm_b32 v250, v247, v246, s32
	v_perm_b32 v251, v249, v248, s32
	global_store_dwordx2 v166, v[250:251], s[100:101] offset:2048 nt
	v_mul_f32_e32 v244, v233, v233
	v_mul_f32_e32 v245, v235, v235
	v_fmac_f32_e32 v244, v232, v232
	v_fmac_f32_e32 v245, v234, v234
	v_add_f32_e32 v244, v244, v245
	v_add_f32_e32 v175, v175, v244
	v_bfe_u32 v246, v232, 16, 1
	v_bfe_u32 v247, v233, 16, 1
	v_bfe_u32 v248, v234, 16, 1
	v_bfe_u32 v249, v235, 16, 1
	v_add3_u32 v246, v232, v246, s75
	v_add3_u32 v247, v233, v247, s75
	v_add3_u32 v248, v234, v248, s75
	v_add3_u32 v249, v235, v249, s75
	v_perm_b32 v250, v247, v246, s32
	v_perm_b32 v251, v249, v248, s32
	global_store_dwordx2 v166, v[250:251], s[100:101] offset:2560 nt
	v_mul_f32_e32 v244, v237, v237
	v_mul_f32_e32 v245, v239, v239
	v_fmac_f32_e32 v244, v236, v236
	v_fmac_f32_e32 v245, v238, v238
	v_add_f32_e32 v244, v244, v245
	v_add_f32_e32 v175, v175, v244
	v_bfe_u32 v246, v236, 16, 1
	v_bfe_u32 v247, v237, 16, 1
	v_bfe_u32 v248, v238, 16, 1
	v_bfe_u32 v249, v239, 16, 1
	v_add3_u32 v246, v236, v246, s75
	v_add3_u32 v247, v237, v247, s75
	v_add3_u32 v248, v238, v248, s75
	v_add3_u32 v249, v239, v249, s75
	v_perm_b32 v250, v247, v246, s32
	v_perm_b32 v251, v249, v248, s32
	global_store_dwordx2 v166, v[250:251], s[100:101] offset:3072 nt
	v_mul_f32_e32 v244, v241, v241
	v_mul_f32_e32 v245, v243, v243
	v_fmac_f32_e32 v244, v240, v240
	v_fmac_f32_e32 v245, v242, v242
	v_add_f32_e32 v244, v244, v245
	v_add_f32_e32 v175, v175, v244
	v_bfe_u32 v246, v240, 16, 1
	v_bfe_u32 v247, v241, 16, 1
	v_bfe_u32 v248, v242, 16, 1
	v_bfe_u32 v249, v243, 16, 1
	v_add3_u32 v246, v240, v246, s75
	v_add3_u32 v247, v241, v247, s75
	v_add3_u32 v248, v242, v248, s75
	v_add3_u32 v249, v243, v249, s75
	v_perm_b32 v250, v247, v246, s32
	v_perm_b32 v251, v249, v248, s32
	global_store_dwordx2 v166, v[250:251], s[100:101] offset:3584 nt
	s_add_u32 s100, s100, 0x800000
	s_addc_u32 s101, s101, 0
	global_load_dwordx4 v[212:215], v164, s[98:99] offset:0 nt
	global_load_dwordx4 v[216:219], v164, s[98:99] offset:1024 nt
	global_load_dwordx4 v[220:223], v164, s[98:99] offset:2048 nt
	global_load_dwordx4 v[224:227], v164, s[98:99] offset:3072 nt
	global_load_dwordx4 v[228:231], v165, s[98:99] offset:0 nt
	global_load_dwordx4 v[232:235], v165, s[98:99] offset:1024 nt
	global_load_dwordx4 v[236:239], v165, s[98:99] offset:2048 nt
	global_load_dwordx4 v[240:243], v165, s[98:99] offset:3072 nt
	s_add_u32 s98, s98, 0x1000000
	s_addc_u32 s99, s99, 0
	s_waitcnt vmcnt(16)
	v_mul_f32_e32 v244, v181, v181
	v_mul_f32_e32 v245, v183, v183
	v_fmac_f32_e32 v244, v180, v180
	v_fmac_f32_e32 v245, v182, v182
	v_add_f32_e32 v178, v244, v245
	v_bfe_u32 v246, v180, 16, 1
	v_bfe_u32 v247, v181, 16, 1
	v_bfe_u32 v248, v182, 16, 1
	v_bfe_u32 v249, v183, 16, 1
	v_add3_u32 v246, v180, v246, s75
	v_add3_u32 v247, v181, v247, s75
	v_add3_u32 v248, v182, v248, s75
	v_add3_u32 v249, v183, v249, s75
	v_perm_b32 v250, v247, v246, s32
	v_perm_b32 v251, v249, v248, s32
	global_store_dwordx2 v166, v[250:251], s[100:101] offset:0 nt
	v_mul_f32_e32 v244, v185, v185
	v_mul_f32_e32 v245, v187, v187
	v_fmac_f32_e32 v244, v184, v184
	v_fmac_f32_e32 v245, v186, v186
	v_add_f32_e32 v244, v244, v245
	v_add_f32_e32 v178, v178, v244
	v_bfe_u32 v246, v184, 16, 1
	v_bfe_u32 v247, v185, 16, 1
	v_bfe_u32 v248, v186, 16, 1
	v_bfe_u32 v249, v187, 16, 1
	v_add3_u32 v246, v184, v246, s75
	v_add3_u32 v247, v185, v247, s75
	v_add3_u32 v248, v186, v248, s75
	v_add3_u32 v249, v187, v249, s75
	v_perm_b32 v250, v247, v246, s32
	v_perm_b32 v251, v249, v248, s32
	global_store_dwordx2 v166, v[250:251], s[100:101] offset:512 nt
	v_mul_f32_e32 v244, v189, v189
	v_mul_f32_e32 v245, v191, v191
	v_fmac_f32_e32 v244, v188, v188
	v_fmac_f32_e32 v245, v190, v190
	v_add_f32_e32 v244, v244, v245
	v_add_f32_e32 v178, v178, v244
	v_bfe_u32 v246, v188, 16, 1
	v_bfe_u32 v247, v189, 16, 1
	v_bfe_u32 v248, v190, 16, 1
	v_bfe_u32 v249, v191, 16, 1
	v_add3_u32 v246, v188, v246, s75
	v_add3_u32 v247, v189, v247, s75
	v_add3_u32 v248, v190, v248, s75
	v_add3_u32 v249, v191, v249, s75
	v_perm_b32 v250, v247, v246, s32
	v_perm_b32 v251, v249, v248, s32
	global_store_dwordx2 v166, v[250:251], s[100:101] offset:1024 nt
	v_mul_f32_e32 v244, v193, v193
	v_mul_f32_e32 v245, v195, v195
	v_fmac_f32_e32 v244, v192, v192
	v_fmac_f32_e32 v245, v194, v194
	v_add_f32_e32 v244, v244, v245
	v_add_f32_e32 v178, v178, v244
	v_bfe_u32 v246, v192, 16, 1
	v_bfe_u32 v247, v193, 16, 1
	v_bfe_u32 v248, v194, 16, 1
	v_bfe_u32 v249, v195, 16, 1
	v_add3_u32 v246, v192, v246, s75
	v_add3_u32 v247, v193, v247, s75
	v_add3_u32 v248, v194, v248, s75
	v_add3_u32 v249, v195, v249, s75
	v_perm_b32 v250, v247, v246, s32
	v_perm_b32 v251, v249, v248, s32
	global_store_dwordx2 v166, v[250:251], s[100:101] offset:1536 nt
	v_mul_f32_e32 v244, v197, v197
	v_mul_f32_e32 v245, v199, v199
	v_fmac_f32_e32 v244, v196, v196
	v_fmac_f32_e32 v245, v198, v198
	v_add_f32_e32 v244, v244, v245
	v_add_f32_e32 v178, v178, v244
	v_bfe_u32 v246, v196, 16, 1
	v_bfe_u32 v247, v197, 16, 1
	v_bfe_u32 v248, v198, 16, 1
	v_bfe_u32 v249, v199, 16, 1
	v_add3_u32 v246, v196, v246, s75
	v_add3_u32 v247, v197, v247, s75
	v_add3_u32 v248, v198, v248, s75
	v_add3_u32 v249, v199, v249, s75
	v_perm_b32 v250, v247, v246, s32
	v_perm_b32 v251, v249, v248, s32
	global_store_dwordx2 v166, v[250:251], s[100:101] offset:2048 nt
	v_mul_f32_e32 v244, v201, v201
	v_mul_f32_e32 v245, v203, v203
	v_fmac_f32_e32 v244, v200, v200
	v_fmac_f32_e32 v245, v202, v202
	v_add_f32_e32 v244, v244, v245
	v_add_f32_e32 v178, v178, v244
	v_bfe_u32 v246, v200, 16, 1
	v_bfe_u32 v247, v201, 16, 1
	v_bfe_u32 v248, v202, 16, 1
	v_bfe_u32 v249, v203, 16, 1
	v_add3_u32 v246, v200, v246, s75
	v_add3_u32 v247, v201, v247, s75
	v_add3_u32 v248, v202, v248, s75
	v_add3_u32 v249, v203, v249, s75
	v_perm_b32 v250, v247, v246, s32
	v_perm_b32 v251, v249, v248, s32
	global_store_dwordx2 v166, v[250:251], s[100:101] offset:2560 nt
	v_mul_f32_e32 v244, v205, v205
	v_mul_f32_e32 v245, v207, v207
	v_fmac_f32_e32 v244, v204, v204
	v_fmac_f32_e32 v245, v206, v206
	v_add_f32_e32 v244, v244, v245
	v_add_f32_e32 v178, v178, v244
	v_bfe_u32 v246, v204, 16, 1
	v_bfe_u32 v247, v205, 16, 1
	v_bfe_u32 v248, v206, 16, 1
	v_bfe_u32 v249, v207, 16, 1
	v_add3_u32 v246, v204, v246, s75
	v_add3_u32 v247, v205, v247, s75
	v_add3_u32 v248, v206, v248, s75
	v_add3_u32 v249, v207, v249, s75
	v_perm_b32 v250, v247, v246, s32
	v_perm_b32 v251, v249, v248, s32
	global_store_dwordx2 v166, v[250:251], s[100:101] offset:3072 nt
	v_mul_f32_e32 v244, v209, v209
	v_mul_f32_e32 v245, v211, v211
	v_fmac_f32_e32 v244, v208, v208
	v_fmac_f32_e32 v245, v210, v210
	v_add_f32_e32 v244, v244, v245
	v_add_f32_e32 v178, v178, v244
	v_bfe_u32 v246, v208, 16, 1
	v_bfe_u32 v247, v209, 16, 1
	v_bfe_u32 v248, v210, 16, 1
	v_bfe_u32 v249, v211, 16, 1
	v_add3_u32 v246, v208, v246, s75
	v_add3_u32 v247, v209, v247, s75
	v_add3_u32 v248, v210, v248, s75
	v_add3_u32 v249, v211, v249, s75
	v_perm_b32 v250, v247, v246, s32
	v_perm_b32 v251, v249, v248, s32
	global_store_dwordx2 v166, v[250:251], s[100:101] offset:3584 nt
	s_add_u32 s100, s100, 0x800000
	s_addc_u32 s101, s101, 0
	s_waitcnt vmcnt(8)
	v_mul_f32_e32 v244, v213, v213
	v_mul_f32_e32 v245, v215, v215
	v_fmac_f32_e32 v244, v212, v212
	v_fmac_f32_e32 v245, v214, v214
	v_add_f32_e32 v255, v244, v245
	v_bfe_u32 v246, v212, 16, 1
	v_bfe_u32 v247, v213, 16, 1
	v_bfe_u32 v248, v214, 16, 1
	v_bfe_u32 v249, v215, 16, 1
	v_add3_u32 v246, v212, v246, s75
	v_add3_u32 v247, v213, v247, s75
	v_add3_u32 v248, v214, v248, s75
	v_add3_u32 v249, v215, v249, s75
	v_perm_b32 v250, v247, v246, s32
	v_perm_b32 v251, v249, v248, s32
	global_store_dwordx2 v166, v[250:251], s[100:101] offset:0 nt
	v_mul_f32_e32 v244, v217, v217
	v_mul_f32_e32 v245, v219, v219
	v_fmac_f32_e32 v244, v216, v216
	v_fmac_f32_e32 v245, v218, v218
	v_add_f32_e32 v244, v244, v245
	v_add_f32_e32 v255, v255, v244
	v_bfe_u32 v246, v216, 16, 1
	v_bfe_u32 v247, v217, 16, 1
	v_bfe_u32 v248, v218, 16, 1
	v_bfe_u32 v249, v219, 16, 1
	v_add3_u32 v246, v216, v246, s75
	v_add3_u32 v247, v217, v247, s75
	v_add3_u32 v248, v218, v248, s75
	v_add3_u32 v249, v219, v249, s75
	v_perm_b32 v250, v247, v246, s32
	v_perm_b32 v251, v249, v248, s32
	global_store_dwordx2 v166, v[250:251], s[100:101] offset:512 nt
	v_mul_f32_e32 v244, v221, v221
	v_mul_f32_e32 v245, v223, v223
	v_fmac_f32_e32 v244, v220, v220
	v_fmac_f32_e32 v245, v222, v222
	v_add_f32_e32 v244, v244, v245
	v_add_f32_e32 v255, v255, v244
	v_bfe_u32 v246, v220, 16, 1
	v_bfe_u32 v247, v221, 16, 1
	v_bfe_u32 v248, v222, 16, 1
	v_bfe_u32 v249, v223, 16, 1
	v_add3_u32 v246, v220, v246, s75
	v_add3_u32 v247, v221, v247, s75
	v_add3_u32 v248, v222, v248, s75
	v_add3_u32 v249, v223, v249, s75
	v_perm_b32 v250, v247, v246, s32
	v_perm_b32 v251, v249, v248, s32
	global_store_dwordx2 v166, v[250:251], s[100:101] offset:1024 nt
	v_mul_f32_e32 v244, v225, v225
	v_mul_f32_e32 v245, v227, v227
	v_fmac_f32_e32 v244, v224, v224
	v_fmac_f32_e32 v245, v226, v226
	v_add_f32_e32 v244, v244, v245
	v_add_f32_e32 v255, v255, v244
	v_bfe_u32 v246, v224, 16, 1
	v_bfe_u32 v247, v225, 16, 1
	v_bfe_u32 v248, v226, 16, 1
	v_bfe_u32 v249, v227, 16, 1
	v_add3_u32 v246, v224, v246, s75
	v_add3_u32 v247, v225, v247, s75
	v_add3_u32 v248, v226, v248, s75
	v_add3_u32 v249, v227, v249, s75
	v_perm_b32 v250, v247, v246, s32
	v_perm_b32 v251, v249, v248, s32
	global_store_dwordx2 v166, v[250:251], s[100:101] offset:1536 nt
	v_mul_f32_e32 v244, v229, v229
	v_mul_f32_e32 v245, v231, v231
	v_fmac_f32_e32 v244, v228, v228
	v_fmac_f32_e32 v245, v230, v230
	v_add_f32_e32 v244, v244, v245
	v_add_f32_e32 v255, v255, v244
	v_bfe_u32 v246, v228, 16, 1
	v_bfe_u32 v247, v229, 16, 1
	v_bfe_u32 v248, v230, 16, 1
	v_bfe_u32 v249, v231, 16, 1
	v_add3_u32 v246, v228, v246, s75
	v_add3_u32 v247, v229, v247, s75
	v_add3_u32 v248, v230, v248, s75
	v_add3_u32 v249, v231, v249, s75
	v_perm_b32 v250, v247, v246, s32
	v_perm_b32 v251, v249, v248, s32
	global_store_dwordx2 v166, v[250:251], s[100:101] offset:2048 nt
	v_mul_f32_e32 v244, v233, v233
	v_mul_f32_e32 v245, v235, v235
	v_fmac_f32_e32 v244, v232, v232
	v_fmac_f32_e32 v245, v234, v234
	v_add_f32_e32 v244, v244, v245
	v_add_f32_e32 v255, v255, v244
	v_bfe_u32 v246, v232, 16, 1
	v_bfe_u32 v247, v233, 16, 1
	v_bfe_u32 v248, v234, 16, 1
	v_bfe_u32 v249, v235, 16, 1
	v_add3_u32 v246, v232, v246, s75
	v_add3_u32 v247, v233, v247, s75
	v_add3_u32 v248, v234, v248, s75
	v_add3_u32 v249, v235, v249, s75
	v_perm_b32 v250, v247, v246, s32
	v_perm_b32 v251, v249, v248, s32
	global_store_dwordx2 v166, v[250:251], s[100:101] offset:2560 nt
	v_mul_f32_e32 v244, v237, v237
	v_mul_f32_e32 v245, v239, v239
	v_fmac_f32_e32 v244, v236, v236
	v_fmac_f32_e32 v245, v238, v238
	v_add_f32_e32 v244, v244, v245
	v_add_f32_e32 v255, v255, v244
	v_bfe_u32 v246, v236, 16, 1
	v_bfe_u32 v247, v237, 16, 1
	v_bfe_u32 v248, v238, 16, 1
	v_bfe_u32 v249, v239, 16, 1
	v_add3_u32 v246, v236, v246, s75
	v_add3_u32 v247, v237, v247, s75
	v_add3_u32 v248, v238, v248, s75
	v_add3_u32 v249, v239, v249, s75
	v_perm_b32 v250, v247, v246, s32
	v_perm_b32 v251, v249, v248, s32
	global_store_dwordx2 v166, v[250:251], s[100:101] offset:3072 nt
	v_mul_f32_e32 v244, v241, v241
	v_mul_f32_e32 v245, v243, v243
	v_fmac_f32_e32 v244, v240, v240
	v_fmac_f32_e32 v245, v242, v242
	v_add_f32_e32 v244, v244, v245
	v_add_f32_e32 v255, v255, v244
	v_bfe_u32 v246, v240, 16, 1
	v_bfe_u32 v247, v241, 16, 1
	v_bfe_u32 v248, v242, 16, 1
	v_bfe_u32 v249, v243, 16, 1
	v_add3_u32 v246, v240, v246, s75
	v_add3_u32 v247, v241, v247, s75
	v_add3_u32 v248, v242, v248, s75
	v_add3_u32 v249, v243, v249, s75
	v_perm_b32 v250, v247, v246, s32
	v_perm_b32 v251, v249, v248, s32
	global_store_dwordx2 v166, v[250:251], s[100:101] offset:3584 nt
	ds_bpermute_b32 v176, v167, v174
	ds_bpermute_b32 v177, v167, v175
	ds_bpermute_b32 v244, v167, v178
	ds_bpermute_b32 v245, v167, v255
	s_waitcnt lgkmcnt(3)
	v_add_f32_e32 v174, v174, v176
	s_waitcnt lgkmcnt(2)
	v_add_f32_e32 v175, v175, v177
	s_waitcnt lgkmcnt(1)
	v_add_f32_e32 v178, v178, v244
	s_waitcnt lgkmcnt(0)
	v_add_f32_e32 v255, v255, v245
	ds_bpermute_b32 v176, v168, v174
	ds_bpermute_b32 v177, v168, v175
	ds_bpermute_b32 v244, v168, v178
	ds_bpermute_b32 v245, v168, v255
	s_waitcnt lgkmcnt(3)
	v_add_f32_e32 v174, v174, v176
	s_waitcnt lgkmcnt(2)
	v_add_f32_e32 v175, v175, v177
	s_waitcnt lgkmcnt(1)
	v_add_f32_e32 v178, v178, v244
	s_waitcnt lgkmcnt(0)
	v_add_f32_e32 v255, v255, v245
	ds_bpermute_b32 v176, v169, v174
	ds_bpermute_b32 v177, v169, v175
	ds_bpermute_b32 v244, v169, v178
	ds_bpermute_b32 v245, v169, v255
	s_waitcnt lgkmcnt(3)
	v_add_f32_e32 v174, v174, v176
	s_waitcnt lgkmcnt(2)
	v_add_f32_e32 v175, v175, v177
	s_waitcnt lgkmcnt(1)
	v_add_f32_e32 v178, v178, v244
	s_waitcnt lgkmcnt(0)
	v_add_f32_e32 v255, v255, v245
	ds_bpermute_b32 v176, v170, v174
	ds_bpermute_b32 v177, v170, v175
	ds_bpermute_b32 v244, v170, v178
	ds_bpermute_b32 v245, v170, v255
	s_waitcnt lgkmcnt(3)
	v_add_f32_e32 v174, v174, v176
	s_waitcnt lgkmcnt(2)
	v_add_f32_e32 v175, v175, v177
	s_waitcnt lgkmcnt(1)
	v_add_f32_e32 v178, v178, v244
	s_waitcnt lgkmcnt(0)
	v_add_f32_e32 v255, v255, v245
	ds_bpermute_b32 v176, v171, v174
	ds_bpermute_b32 v177, v171, v175
	ds_bpermute_b32 v244, v171, v178
	ds_bpermute_b32 v245, v171, v255
	s_waitcnt lgkmcnt(3)
	v_add_f32_e32 v174, v174, v176
	s_waitcnt lgkmcnt(2)
	v_add_f32_e32 v175, v175, v177
	s_waitcnt lgkmcnt(1)
	v_add_f32_e32 v178, v178, v244
	s_waitcnt lgkmcnt(0)
	v_add_f32_e32 v255, v255, v245
	ds_bpermute_b32 v176, v172, v174
	ds_bpermute_b32 v177, v172, v175
	ds_bpermute_b32 v244, v172, v178
	ds_bpermute_b32 v245, v172, v255
	s_waitcnt lgkmcnt(3)
	v_add_f32_e32 v174, v174, v176
	s_waitcnt lgkmcnt(2)
	v_add_f32_e32 v175, v175, v177
	s_waitcnt lgkmcnt(1)
	v_add_f32_e32 v178, v178, v244
	s_waitcnt lgkmcnt(0)
	v_add_f32_e32 v255, v255, v245
	s_mov_b64 s[42:43], exec
	s_mov_b64 exec, 1
	global_store_dword v173, v174, s[54:55]
	s_add_u32 s54, s54, 0x2000
	s_addc_u32 s55, s55, 0
	global_store_dword v173, v175, s[54:55]
	s_add_u32 s54, s54, 0x2000
	s_addc_u32 s55, s55, 0
	global_store_dword v173, v178, s[54:55]
	s_add_u32 s54, s54, 0x2000
	s_addc_u32 s55, s55, 0
	global_store_dword v173, v255, s[54:55]
	s_mov_b64 exec, s[42:43]
	s_branch .LBB0_20

	.amdhsa_kernel _Z14fwd_megakernel6Params
		.amdhsa_group_segment_fixed_size 0
		.amdhsa_private_segment_fixed_size 0
		.amdhsa_kernarg_size 528
		.amdhsa_user_sgpr_count 2
		.amdhsa_user_sgpr_dispatch_ptr 0
		.amdhsa_user_sgpr_queue_ptr 0
		.amdhsa_user_sgpr_kernarg_segment_ptr 1
		.amdhsa_user_sgpr_dispatch_id 0
		.amdhsa_user_sgpr_kernarg_preload_length 0
		.amdhsa_user_sgpr_kernarg_preload_offset 0
		.amdhsa_user_sgpr_private_segment_size 0
		.amdhsa_uses_dynamic_stack 0
		.amdhsa_enable_private_segment 0
		.amdhsa_system_sgpr_workgroup_id_x 1
		.amdhsa_system_sgpr_workgroup_id_y 0
		.amdhsa_system_sgpr_workgroup_id_z 0
		.amdhsa_system_sgpr_workgroup_info 0
		.amdhsa_system_vgpr_workitem_id 2
		.amdhsa_next_free_vgpr 256
		.amdhsa_next_free_sgpr 102
		.amdhsa_accum_offset 256
		.amdhsa_reserve_vcc 1
		.amdhsa_float_round_mode_32 0
		.amdhsa_float_round_mode_16_64 0
		.amdhsa_float_denorm_mode_32 3
		.amdhsa_float_denorm_mode_16_64 3
		.amdhsa_dx10_clamp 1
		.amdhsa_ieee_mode 1
		.amdhsa_fp16_overflow 0
		.amdhsa_tg_split 0
		.amdhsa_exception_fp_ieee_invalid_op 0
		.amdhsa_exception_fp_denorm_src 0
		.amdhsa_exception_fp_ieee_div_zero 0
		.amdhsa_exception_fp_ieee_overflow 0
		.amdhsa_exception_fp_ieee_underflow 0
		.amdhsa_exception_fp_ieee_inexact 0
		.amdhsa_exception_int_div_zero 0
	.end_amdhsa_kernel

amdhsa.kernels:
  - .agpr_count:     0
    .args:
      - .offset:         0
        .size:           272
        .value_kind:     by_value
      - .offset:         272
        .size:           4
        .value_kind:     hidden_block_count_x
      - .offset:         276
        .size:           4
        .value_kind:     hidden_block_count_y
      - .offset:         280
        .size:           4
        .value_kind:     hidden_block_count_z
      - .offset:         284
        .size:           2
        .value_kind:     hidden_group_size_x
      - .offset:         286
        .size:           2
        .value_kind:     hidden_group_size_y
      - .offset:         288
        .size:           2
        .value_kind:     hidden_group_size_z
      - .offset:         290
        .size:           2
        .value_kind:     hidden_remainder_x
      - .offset:         292
        .size:           2
        .value_kind:     hidden_remainder_y
      - .offset:         294
        .size:           2
        .value_kind:     hidden_remainder_z
      - .offset:         312
        .size:           8
        .value_kind:     hidden_global_offset_x
      - .offset:         320
        .size:           8
        .value_kind:     hidden_global_offset_y
      - .offset:         328
        .size:           8
        .value_kind:     hidden_global_offset_z
      - .offset:         336
        .size:           2
        .value_kind:     hidden_grid_dims
      - .offset:         360
        .size:           8
        .value_kind:     hidden_multigrid_sync_arg
      - .offset:         392
        .size:           4
        .value_kind:     hidden_dynamic_lds_size
    .group_segment_fixed_size: 0
    .kernarg_segment_align: 8
    .kernarg_segment_size: 528
    .language:       OpenCL C
    .language_version:
      - 2
      - 0
    .max_flat_workgroup_size: 512
    .name:           _Z14fwd_megakernel6Params
    .private_segment_fixed_size: 0
    .sgpr_count:     108
    .sgpr_spill_count: 181
    .symbol:         _Z14fwd_megakernel6Params.kd
    .uniform_work_group_size: 1
    .uses_dynamic_stack: false
    .vgpr_count:     256
    .vgpr_spill_count: 0
    .wavefront_size: 64
